# final RMSNorm double-buffered with counted waits that do not include the previous row's stores; all LDS pointer-table fetches via ds_read_b64
# baseline (speedup 1.0000x reference)
; #define TIDX tid_opaque()
; __device__ void rmsnorm_phase(const float* src, const float* g, float* copy_dst, bf16_t* xn, float* outf) {
;     const int lane = TIDX & 63, gw = blockIdx.x * 8 + (TIDX >> 6), nw = gridDim.x * 8;
;     f32x4 gv[4];
; #pragma unroll
;     for (int j = 0; j < 4; ++j) gv[j] = ((const f32x4*)g)[lane + 64 * j];
;     for (int row = gw; row < MT; row += nw) {
;         const f32x4* pr = (const f32x4*)(src + (size_t)row * DM); f32x4 v[4]; float ss = 0.f;
; #pragma unroll
;         for (int j = 0; j < 4; ++j) { v[j] = pr[lane + 64 * j]; ss += v[j][0] * v[j][0] + v[j][1] * v[j][1] + v[j][2] * v[j][2] + v[j][3] * v[j][3]; }
.LBB0_838:
	s_and_b64 vcc, exec, s[0:1]
	s_cbranch_vccz .LBB0_5
	s_add_i32 s0, 0, 0x23f20
	s_cmp_lg_u32 s0, -1
	s_cselect_b32 s0, s0, 0
	s_cselect_b32 s1, s41, 0
	s_waitcnt vmcnt(3)
	v_mov_b32_e32 v0, s0
	v_mov_b32_e32 v1, s1
	ds_read_b64 v[2:3], v0
	s_waitcnt vmcnt(0) lgkmcnt(0)
	v_mov_b32_e32 v0, v234
	v_mov_b32_e32 v1, v234
	s_mov_b32 s5, 0x8000
	v_ashrrev_i32_e32 v1, 6, v1
	v_add_u32_e32 v32, s77, v1
	v_cmp_gt_i32_e32 vcc, s5, v32
	s_waitcnt lgkmcnt(0)
	v_readfirstlane_b32 s1, v3
	v_readfirstlane_b32 s0, v2
	s_and_saveexec_b64 s[6:7], vcc
	s_cbranch_execz .LBB0_4
	v_lshlrev_b32_e32 v0, 4, v0
	v_and_b32_e32 v18, 0x3f0, v0
	s_nop 0
	global_load_dwordx4 v[0:3], v18, s[0:1]
	global_load_dwordx4 v[4:7], v18, s[0:1] offset:1024
	global_load_dwordx4 v[8:11], v18, s[0:1] offset:2048
	global_load_dwordx4 v[12:15], v18, s[0:1] offset:3072
	v_and_b32_e32 v16, 64, v243
	v_add_u32_e32 v16, 64, v16
	v_xor_b32_e32 v17, 32, v243
	v_cmp_lt_i32_e32 vcc, v17, v16
	v_readlane_b32 s0, v254, 19
	v_readlane_b32 s1, v254, 20
	v_cndmask_b32_e32 v17, v243, v17, vcc
	v_lshlrev_b32_e32 v36, 2, v17
	v_xor_b32_e32 v17, 16, v243
	v_cmp_lt_i32_e32 vcc, v17, v16
	s_load_dword s0, s[0:1], 0x0
	v_ashrrev_i32_e32 v33, 31, v32
	v_cndmask_b32_e32 v17, v243, v17, vcc
	v_lshlrev_b32_e32 v37, 2, v17
	v_xor_b32_e32 v17, 8, v243
	v_cmp_lt_i32_e32 vcc, v17, v16
	s_waitcnt lgkmcnt(0)
	s_lshl_b32 s8, s0, 3
	v_readlane_b32 s0, v255, 22
	v_cndmask_b32_e32 v17, v243, v17, vcc
	v_lshlrev_b32_e32 v38, 2, v17
	v_xor_b32_e32 v17, 4, v243
	v_cmp_lt_i32_e32 vcc, v17, v16
	v_readlane_b32 s1, v255, 23
	s_ashr_i32 s9, s8, 31
	v_cndmask_b32_e32 v17, v243, v17, vcc
	v_lshlrev_b32_e32 v39, 2, v17
	v_xor_b32_e32 v17, 2, v243
	v_cmp_lt_i32_e32 vcc, v17, v16
	s_lshl_b64 s[10:11], s[8:9], 12
	s_mov_b64 s[12:13], 0
	v_cndmask_b32_e32 v17, v243, v17, vcc
	v_lshlrev_b32_e32 v40, 2, v17
	v_xor_b32_e32 v17, 1, v243
	v_cmp_lt_i32_e32 vcc, v17, v16
	s_nop 1
	v_cndmask_b32_e32 v16, v243, v17, vcc
	v_lshlrev_b32_e32 v41, 2, v16
	v_lshlrev_b64 v[16:17], 12, v[32:33]
	v_or_b32_e32 v16, v16, v18
	v_lshl_add_u64 v[34:35], s[0:1], 0, v[16:17]
	global_load_dwordx4 v[28:31], v[34:35], off offset:-3072
	global_load_dwordx4 v[24:27], v[34:35], off offset:-2048
	global_load_dwordx4 v[20:23], v[34:35], off offset:-1024
	global_load_dwordx4 v[16:19], v[34:35], off
	s_waitcnt vmcnt(0)
	s_branch .Lrn_A

; __device__ __forceinline__ unsigned cvt_pk_bf16(float lo, float hi) { const f32x2_t v = {lo, hi}; const bf16x2_t b = __builtin_convertvector(v, bf16x2_t); return __builtin_bit_cast(unsigned, b); }
; __device__ void rmsnorm_phase(const float* src, const float* g, float* copy_dst, bf16_t* xn, float* outf) {
;     ...
;         const f32x4* pr = (const f32x4*)(src + (size_t)row * DM); f32x4 v[4]; float ss = 0.f;
; #pragma unroll
;         for (int j = 0; j < 4; ++j) { v[j] = pr[lane + 64 * j]; ss += v[j][0] * v[j][0] + v[j][1] * v[j][1] + v[j][2] * v[j][2] + v[j][3] * v[j][3]; }
; #pragma unroll
;         for (int o = 32; o >= 1; o >>= 1) ss += __shfl_xor(ss, o);
;         const float r = 1.0f / sqrtf(ss * (1.0f / DM) + 1e-6f);
; #pragma unroll
;         for (int j = 0; j < 4; ++j) { const f32x4 y = v[j] * r * gv[j];
;             if (copy_dst) ((f32x4*)(copy_dst + (size_t)row * DM))[lane + 64 * j] = v[j];
;             if (xn) { u32x2 w; w.x = cvt_pk_bf16(y[0], y[1]); w.y = cvt_pk_bf16(y[2], y[3]); ((u32x2*)(xn + (size_t)row * DM))[lane + 64 * j] = w; }
;             if (outf) ((f32x4*)(outf + (size_t)row * DM))[lane + 64 * j] = y; }
.Lrn_A_np:
	s_waitcnt vmcnt(4)
.Lrn_A_go:
	s_andn2_b64 vcc, exec, s[86:87]
	s_waitcnt vmcnt(11)
	v_mul_f32_e32 v33, v29, v29
	s_waitcnt vmcnt(10) lgkmcnt(0)
	v_mul_f32_e32 v42, v25, v25
	s_waitcnt vmcnt(9)
	v_mul_f32_e32 v43, v21, v21
	v_fmac_f32_e32 v33, v28, v28
	v_fmac_f32_e32 v42, v24, v24
	s_waitcnt vmcnt(8)
	v_mul_f32_e32 v44, v17, v17
	v_fmac_f32_e32 v43, v20, v20
	v_fmac_f32_e32 v33, v30, v30
	v_fmac_f32_e32 v42, v26, v26
	v_fmac_f32_e32 v44, v16, v16
	v_fmac_f32_e32 v43, v22, v22
	v_fmac_f32_e32 v33, v31, v31
	v_fmac_f32_e32 v42, v27, v27
	v_fmac_f32_e32 v44, v18, v18
	v_fmac_f32_e32 v43, v23, v23
	v_add_f32_e32 v33, v33, v42
	v_add_f32_e32 v33, v33, v43
	v_fmac_f32_e32 v44, v19, v19
	v_add_f32_e32 v33, v33, v44
	ds_bpermute_b32 v42, v36, v33
	s_waitcnt lgkmcnt(0)
	v_add_f32_e32 v33, v33, v42
	ds_bpermute_b32 v42, v37, v33
	s_waitcnt lgkmcnt(0)
	v_add_f32_e32 v33, v33, v42
	ds_bpermute_b32 v42, v38, v33
	s_waitcnt lgkmcnt(0)
	v_add_f32_e32 v33, v33, v42
	ds_bpermute_b32 v42, v39, v33
	s_waitcnt lgkmcnt(0)
	v_add_f32_e32 v33, v33, v42
	ds_bpermute_b32 v42, v40, v33
	s_waitcnt lgkmcnt(0)
	v_add_f32_e32 v33, v33, v42
	ds_bpermute_b32 v42, v41, v33
	s_cbranch_vccnz .Lrn_A_lt
	s_waitcnt lgkmcnt(0)
	v_add_f32_e32 v33, v33, v42
	v_fmamk_f32 v33, v33, 0x3a800000, v235
	s_mov_b32 s0, 0xf800000
	v_mul_f32_e32 v42, 0x4f800000, v33
	v_cmp_gt_f32_e32 vcc, s0, v33
	s_nop 1
	v_cndmask_b32_e32 v33, v33, v42, vcc
	v_sqrt_f32_e32 v42, v33
	s_nop 0
	v_add_u32_e32 v43, -1, v42
	v_fma_f32 v45, -v43, v42, v33
	v_add_u32_e32 v44, 1, v42
	v_cmp_ge_f32_e64 s[0:1], 0, v45
	s_nop 1
	v_cndmask_b32_e64 v43, v42, v43, s[0:1]
	v_fma_f32 v42, -v44, v42, v33
	v_cmp_lt_f32_e64 s[0:1], 0, v42
	s_nop 1
	v_cndmask_b32_e64 v42, v43, v44, s[0:1]
	v_mul_f32_e32 v43, 0x37800000, v42
	v_cndmask_b32_e32 v42, v42, v43, vcc
	v_cmp_class_f32_e32 vcc, v33, v236
	s_nop 1
	v_cndmask_b32_e32 v33, v42, v33, vcc
	v_div_scale_f32 v42, s[0:1], v33, v33, 1.0
	v_rcp_f32_e32 v43, v42
	s_nop 0
	v_fma_f32 v44, -v42, v43, 1.0
	v_fmac_f32_e32 v43, v44, v43
	v_div_scale_f32 v44, vcc, 1.0, v33, 1.0
	v_mul_f32_e32 v45, v44, v43
	v_fma_f32 v46, -v42, v45, v44
	v_fmac_f32_e32 v45, v46, v43
	v_fma_f32 v42, -v42, v45, v44
	v_div_fmas_f32 v42, v42, v43, v45
	v_div_fixup_f32 v42, v42, v33, 1.0
	v_pk_mul_f32 v[28:29], v[28:29], v[42:43] op_sel_hi:[1,0]
	v_pk_mul_f32 v[30:31], v[30:31], v[42:43] op_sel_hi:[1,0]
	v_pk_mul_f32 v[24:25], v[24:25], v[42:43] op_sel_hi:[1,0]
	v_pk_mul_f32 v[26:27], v[26:27], v[42:43] op_sel_hi:[1,0]
	v_pk_mul_f32 v[20:21], v[20:21], v[42:43] op_sel_hi:[1,0]
	v_pk_mul_f32 v[22:23], v[22:23], v[42:43] op_sel_hi:[1,0]
	v_pk_mul_f32 v[16:17], v[16:17], v[42:43] op_sel_hi:[1,0]
	v_pk_mul_f32 v[18:19], v[18:19], v[42:43] op_sel_hi:[1,0]
	v_pk_mul_f32 v[30:31], v[2:3], v[30:31]
	v_pk_mul_f32 v[28:29], v[0:1], v[28:29]
	v_pk_mul_f32 v[26:27], v[6:7], v[26:27]
	v_pk_mul_f32 v[24:25], v[4:5], v[24:25]
	v_pk_mul_f32 v[22:23], v[10:11], v[22:23]
	v_pk_mul_f32 v[20:21], v[8:9], v[20:21]
	v_pk_mul_f32 v[18:19], v[14:15], v[18:19]
	v_pk_mul_f32 v[16:17], v[12:13], v[16:17]
	global_store_dwordx4 v[34:35], v[28:31], off offset:-3072
	global_store_dwordx4 v[34:35], v[24:27], off offset:-2048
	global_store_dwordx4 v[34:35], v[20:23], off offset:-1024
	global_store_dwordx4 v[34:35], v[16:19], off

; __device__ __forceinline__ unsigned cvt_pk_bf16(float lo, float hi) { const f32x2_t v = {lo, hi}; const bf16x2_t b = __builtin_convertvector(v, bf16x2_t); return __builtin_bit_cast(unsigned, b); }
; __device__ void rmsnorm_phase(const float* src, const float* g, float* copy_dst, bf16_t* xn, float* outf) {
;     ...
;         const f32x4* pr = (const f32x4*)(src + (size_t)row * DM); f32x4 v[4]; float ss = 0.f;
; #pragma unroll
;         for (int j = 0; j < 4; ++j) { v[j] = pr[lane + 64 * j]; ss += v[j][0] * v[j][0] + v[j][1] * v[j][1] + v[j][2] * v[j][2] + v[j][3] * v[j][3]; }
; #pragma unroll
;         for (int o = 32; o >= 1; o >>= 1) ss += __shfl_xor(ss, o);
;         const float r = 1.0f / sqrtf(ss * (1.0f / DM) + 1e-6f);
; #pragma unroll
;         for (int j = 0; j < 4; ++j) { const f32x4 y = v[j] * r * gv[j];
;             if (copy_dst) ((f32x4*)(copy_dst + (size_t)row * DM))[lane + 64 * j] = v[j];
;             if (xn) { u32x2 w; w.x = cvt_pk_bf16(y[0], y[1]); w.y = cvt_pk_bf16(y[2], y[3]); ((u32x2*)(xn + (size_t)row * DM))[lane + 64 * j] = w; }
;             if (outf) ((f32x4*)(outf + (size_t)row * DM))[lane + 64 * j] = y; }
.Lrn_B_go:
	s_andn2_b64 vcc, exec, s[86:87]
	s_waitcnt vmcnt(11)
	v_mul_f32_e32 v33, v61, v61
	s_waitcnt vmcnt(10) lgkmcnt(0)
	v_mul_f32_e32 v42, v57, v57
	s_waitcnt vmcnt(9)
	v_mul_f32_e32 v43, v53, v53
	v_fmac_f32_e32 v33, v60, v60
	v_fmac_f32_e32 v42, v56, v56
	s_waitcnt vmcnt(8)
	v_mul_f32_e32 v44, v49, v49
	v_fmac_f32_e32 v43, v52, v52
	v_fmac_f32_e32 v33, v62, v62
	v_fmac_f32_e32 v42, v58, v58
	v_fmac_f32_e32 v44, v48, v48
	v_fmac_f32_e32 v43, v54, v54
	v_fmac_f32_e32 v33, v63, v63
	v_fmac_f32_e32 v42, v59, v59
	v_fmac_f32_e32 v44, v50, v50
	v_fmac_f32_e32 v43, v55, v55
	v_add_f32_e32 v33, v33, v42
	v_add_f32_e32 v33, v33, v43
	v_fmac_f32_e32 v44, v51, v51
	v_add_f32_e32 v33, v33, v44
	ds_bpermute_b32 v42, v36, v33
	s_waitcnt lgkmcnt(0)
	v_add_f32_e32 v33, v33, v42
	ds_bpermute_b32 v42, v37, v33
	s_waitcnt lgkmcnt(0)
	v_add_f32_e32 v33, v33, v42
	ds_bpermute_b32 v42, v38, v33
	s_waitcnt lgkmcnt(0)
	v_add_f32_e32 v33, v33, v42
	ds_bpermute_b32 v42, v39, v33
	s_waitcnt lgkmcnt(0)
	v_add_f32_e32 v33, v33, v42
	ds_bpermute_b32 v42, v40, v33
	s_waitcnt lgkmcnt(0)
	v_add_f32_e32 v33, v33, v42
	ds_bpermute_b32 v42, v41, v33
	s_cbranch_vccnz .Lrn_B_lt
	s_waitcnt lgkmcnt(0)
	v_add_f32_e32 v33, v33, v42
	v_fmamk_f32 v33, v33, 0x3a800000, v235
	s_mov_b32 s0, 0xf800000
	v_mul_f32_e32 v42, 0x4f800000, v33
	v_cmp_gt_f32_e32 vcc, s0, v33
	s_nop 1
	v_cndmask_b32_e32 v33, v33, v42, vcc
	v_sqrt_f32_e32 v42, v33
	s_nop 0
	v_add_u32_e32 v43, -1, v42
	v_fma_f32 v45, -v43, v42, v33
	v_add_u32_e32 v44, 1, v42
	v_cmp_ge_f32_e64 s[0:1], 0, v45
	s_nop 1
	v_cndmask_b32_e64 v43, v42, v43, s[0:1]
	v_fma_f32 v42, -v44, v42, v33
	v_cmp_lt_f32_e64 s[0:1], 0, v42
	s_nop 1
	v_cndmask_b32_e64 v42, v43, v44, s[0:1]
	v_mul_f32_e32 v43, 0x37800000, v42
	v_cndmask_b32_e32 v42, v42, v43, vcc
	v_cmp_class_f32_e32 vcc, v33, v236
	s_nop 1
	v_cndmask_b32_e32 v33, v42, v33, vcc
	v_div_scale_f32 v42, s[0:1], v33, v33, 1.0
	v_rcp_f32_e32 v43, v42
	s_nop 0
	v_fma_f32 v44, -v42, v43, 1.0
	v_fmac_f32_e32 v43, v44, v43
	v_div_scale_f32 v44, vcc, 1.0, v33, 1.0
	v_mul_f32_e32 v45, v44, v43
	v_fma_f32 v46, -v42, v45, v44
	v_fmac_f32_e32 v45, v46, v43
	v_fma_f32 v42, -v42, v45, v44
	v_div_fmas_f32 v42, v42, v43, v45
	v_div_fixup_f32 v42, v42, v33, 1.0
	v_pk_mul_f32 v[60:61], v[60:61], v[42:43] op_sel_hi:[1,0]
	v_pk_mul_f32 v[62:63], v[62:63], v[42:43] op_sel_hi:[1,0]
	v_pk_mul_f32 v[56:57], v[56:57], v[42:43] op_sel_hi:[1,0]
	v_pk_mul_f32 v[58:59], v[58:59], v[42:43] op_sel_hi:[1,0]
	v_pk_mul_f32 v[52:53], v[52:53], v[42:43] op_sel_hi:[1,0]
	v_pk_mul_f32 v[54:55], v[54:55], v[42:43] op_sel_hi:[1,0]
	v_pk_mul_f32 v[48:49], v[48:49], v[42:43] op_sel_hi:[1,0]
	v_pk_mul_f32 v[50:51], v[50:51], v[42:43] op_sel_hi:[1,0]
	v_pk_mul_f32 v[62:63], v[2:3], v[62:63]
	v_pk_mul_f32 v[60:61], v[0:1], v[60:61]
	v_pk_mul_f32 v[58:59], v[6:7], v[58:59]
	v_pk_mul_f32 v[56:57], v[4:5], v[56:57]
	v_pk_mul_f32 v[54:55], v[10:11], v[54:55]
	v_pk_mul_f32 v[52:53], v[8:9], v[52:53]
	v_pk_mul_f32 v[50:51], v[14:15], v[50:51]
	v_pk_mul_f32 v[48:49], v[12:13], v[48:49]
	global_store_dwordx4 v[34:35], v[60:63], off offset:-3072
	global_store_dwordx4 v[34:35], v[56:59], off offset:-2048
	global_store_dwordx4 v[34:35], v[52:55], off offset:-1024
	global_store_dwordx4 v[34:35], v[48:51], off
